# sc1 (agent-scope write-through) on the 8 SwiGLU ACT stores instead of nt: no dirty ACT lines left for the barrier's buffer_wbl2
# speedup vs baseline: 1.0015x; 1.0015x over previous
.LBB0_255:
	v_mov_b32_e32 v178, 0xbfb8aa3b
	v_mov_b32_e32 v179, 0xbfb8aa3b
	s_lshl_b32 s11, s18, 8
	s_mov_b64 s[18:19], -1
	ds_read_b32 v182, v170
	ds_read_b32 v183, v170 offset:64
	ds_read_b32 v184, v170 offset:128
	ds_read_b32 v185, v170 offset:192
	ds_read_b32 v186, v170 offset:512
	ds_read_b32 v187, v170 offset:576
	ds_read_b32 v188, v170 offset:640
	ds_read_b32 v189, v170 offset:704
	v_add_u32_e32 v203, s11, v166
	v_lshl_or_b32 v202, s60, 7, v171
	v_lshlrev_b32_e32 v202, 1, v202
	v_mad_u32_u24 v202, v203, s86, v202
	s_waitcnt lgkmcnt(0)
	v_pk_fma_f32 v[132:133], v[132:133], v[182:183], v[238:239] op_sel_hi:[1,0,1]
	v_pk_fma_f32 v[134:135], v[134:135], v[182:183], v[240:241] op_sel_hi:[1,0,1]
	v_pk_fma_f32 v[124:125], v[124:125], v[182:183], v[242:243] op_sel_hi:[1,0,1]
	v_pk_fma_f32 v[126:127], v[126:127], v[182:183], v[244:245] op_sel_hi:[1,0,1]
	v_pk_fma_f32 v[128:129], v[128:129], v[182:183], v[246:247] op_sel_hi:[1,0,1]
	v_pk_fma_f32 v[130:131], v[130:131], v[182:183], v[248:249] op_sel_hi:[1,0,1]
	v_pk_fma_f32 v[120:121], v[120:121], v[182:183], v[250:251] op_sel_hi:[1,0,1]
	v_pk_fma_f32 v[122:123], v[122:123], v[182:183], v[252:253] op_sel_hi:[1,0,1]
	v_pk_mul_f32 v[190:191], v[132:133], v[178:179]
	v_pk_mul_f32 v[192:193], v[134:135], v[178:179]
	v_pk_mul_f32 v[194:195], v[124:125], v[178:179]
	v_pk_mul_f32 v[196:197], v[126:127], v[178:179]
	v_exp_f32_e32 v190, v190
	v_exp_f32_e32 v191, v191
	v_exp_f32_e32 v192, v192
	v_exp_f32_e32 v193, v193
	v_exp_f32_e32 v194, v194
	v_exp_f32_e32 v195, v195
	v_exp_f32_e32 v196, v196
	v_exp_f32_e32 v197, v197
	v_pk_add_f32 v[190:191], v[190:191], 1.0 op_sel_hi:[1,0]
	v_pk_add_f32 v[192:193], v[192:193], 1.0 op_sel_hi:[1,0]
	v_pk_add_f32 v[194:195], v[194:195], 1.0 op_sel_hi:[1,0]
	v_pk_add_f32 v[196:197], v[196:197], 1.0 op_sel_hi:[1,0]
	v_rcp_f32_e32 v190, v190
	v_rcp_f32_e32 v191, v191
	v_rcp_f32_e32 v192, v192
	v_rcp_f32_e32 v193, v193
	v_rcp_f32_e32 v194, v194
	v_rcp_f32_e32 v195, v195
	v_rcp_f32_e32 v196, v196
	v_rcp_f32_e32 v197, v197
	v_pk_mul_f32 v[132:133], v[132:133], v[190:191]
	v_pk_mul_f32 v[134:135], v[134:135], v[192:193]
	v_pk_mul_f32 v[124:125], v[124:125], v[194:195]
	v_pk_mul_f32 v[126:127], v[126:127], v[196:197]
	v_pk_mul_f32 v[132:133], v[132:133], v[128:129]
	v_pk_mul_f32 v[134:135], v[134:135], v[130:131]
	v_pk_mul_f32 v[124:125], v[124:125], v[120:121]
	v_pk_mul_f32 v[126:127], v[126:127], v[122:123]
	v_cvt_pk_bf16_f32 v198, v132, v133
	v_cvt_pk_bf16_f32 v199, v134, v135
	v_cvt_pk_bf16_f32 v200, v124, v125
	v_cvt_pk_bf16_f32 v201, v126, v127
	global_store_dwordx4 v202, v[198:201], s[6:7] sc1
	v_pk_fma_f32 v[116:117], v[116:117], v[182:183], v[238:239] op_sel:[0,1,0] op_sel_hi:[1,1,1]
	v_pk_fma_f32 v[118:119], v[118:119], v[182:183], v[240:241] op_sel:[0,1,0] op_sel_hi:[1,1,1]
	v_pk_fma_f32 v[112:113], v[112:113], v[182:183], v[242:243] op_sel:[0,1,0] op_sel_hi:[1,1,1]
	v_pk_fma_f32 v[114:115], v[114:115], v[182:183], v[244:245] op_sel:[0,1,0] op_sel_hi:[1,1,1]
	v_pk_fma_f32 v[108:109], v[108:109], v[182:183], v[246:247] op_sel:[0,1,0] op_sel_hi:[1,1,1]
	v_pk_fma_f32 v[110:111], v[110:111], v[182:183], v[248:249] op_sel:[0,1,0] op_sel_hi:[1,1,1]
	v_pk_fma_f32 v[104:105], v[104:105], v[182:183], v[250:251] op_sel:[0,1,0] op_sel_hi:[1,1,1]
	v_pk_fma_f32 v[106:107], v[106:107], v[182:183], v[252:253] op_sel:[0,1,0] op_sel_hi:[1,1,1]
	v_pk_mul_f32 v[190:191], v[116:117], v[178:179]
	v_pk_mul_f32 v[192:193], v[118:119], v[178:179]
	v_pk_mul_f32 v[194:195], v[112:113], v[178:179]
	v_pk_mul_f32 v[196:197], v[114:115], v[178:179]
	v_exp_f32_e32 v190, v190
	v_exp_f32_e32 v191, v191
	v_exp_f32_e32 v192, v192
	v_exp_f32_e32 v193, v193
	v_exp_f32_e32 v194, v194
	v_exp_f32_e32 v195, v195
	v_exp_f32_e32 v196, v196
	v_exp_f32_e32 v197, v197
	v_pk_add_f32 v[190:191], v[190:191], 1.0 op_sel_hi:[1,0]
	v_pk_add_f32 v[192:193], v[192:193], 1.0 op_sel_hi:[1,0]
	v_pk_add_f32 v[194:195], v[194:195], 1.0 op_sel_hi:[1,0]
	v_pk_add_f32 v[196:197], v[196:197], 1.0 op_sel_hi:[1,0]
	v_rcp_f32_e32 v190, v190
	v_rcp_f32_e32 v191, v191
	v_rcp_f32_e32 v192, v192
	v_rcp_f32_e32 v193, v193
	v_rcp_f32_e32 v194, v194
	v_rcp_f32_e32 v195, v195
	v_rcp_f32_e32 v196, v196
	v_rcp_f32_e32 v197, v197
	v_pk_mul_f32 v[116:117], v[116:117], v[190:191]
	v_pk_mul_f32 v[118:119], v[118:119], v[192:193]
	v_pk_mul_f32 v[112:113], v[112:113], v[194:195]
	v_pk_mul_f32 v[114:115], v[114:115], v[196:197]
	v_pk_mul_f32 v[116:117], v[116:117], v[108:109]
	v_pk_mul_f32 v[118:119], v[118:119], v[110:111]
	v_pk_mul_f32 v[112:113], v[112:113], v[104:105]
	v_pk_mul_f32 v[114:115], v[114:115], v[106:107]
	v_cvt_pk_bf16_f32 v198, v116, v117
	v_cvt_pk_bf16_f32 v199, v118, v119
	v_cvt_pk_bf16_f32 v200, v112, v113
	v_cvt_pk_bf16_f32 v201, v114, v115
	v_add_u32_e32 v203, 0x16000, v202
	s_nop 0
	global_store_dwordx4 v203, v[198:201], s[6:7] sc1
	v_pk_fma_f32 v[100:101], v[100:101], v[184:185], v[238:239] op_sel_hi:[1,0,1]
	v_pk_fma_f32 v[102:103], v[102:103], v[184:185], v[240:241] op_sel_hi:[1,0,1]
	v_pk_fma_f32 v[96:97], v[96:97], v[184:185], v[242:243] op_sel_hi:[1,0,1]
	v_pk_fma_f32 v[98:99], v[98:99], v[184:185], v[244:245] op_sel_hi:[1,0,1]
	v_pk_fma_f32 v[92:93], v[92:93], v[184:185], v[246:247] op_sel_hi:[1,0,1]
	v_pk_fma_f32 v[94:95], v[94:95], v[184:185], v[248:249] op_sel_hi:[1,0,1]
	v_pk_fma_f32 v[88:89], v[88:89], v[184:185], v[250:251] op_sel_hi:[1,0,1]
	v_pk_fma_f32 v[90:91], v[90:91], v[184:185], v[252:253] op_sel_hi:[1,0,1]
	v_pk_mul_f32 v[190:191], v[100:101], v[178:179]
	v_pk_mul_f32 v[192:193], v[102:103], v[178:179]
	v_pk_mul_f32 v[194:195], v[96:97], v[178:179]
	v_pk_mul_f32 v[196:197], v[98:99], v[178:179]
	v_exp_f32_e32 v190, v190
	v_exp_f32_e32 v191, v191
	v_exp_f32_e32 v192, v192
	v_exp_f32_e32 v193, v193
	v_exp_f32_e32 v194, v194
	v_exp_f32_e32 v195, v195
	v_exp_f32_e32 v196, v196
	v_exp_f32_e32 v197, v197
	v_pk_add_f32 v[190:191], v[190:191], 1.0 op_sel_hi:[1,0]
	v_pk_add_f32 v[192:193], v[192:193], 1.0 op_sel_hi:[1,0]
	v_pk_add_f32 v[194:195], v[194:195], 1.0 op_sel_hi:[1,0]
	v_pk_add_f32 v[196:197], v[196:197], 1.0 op_sel_hi:[1,0]
	v_rcp_f32_e32 v190, v190
	v_rcp_f32_e32 v191, v191
	v_rcp_f32_e32 v192, v192
	v_rcp_f32_e32 v193, v193
	v_rcp_f32_e32 v194, v194
	v_rcp_f32_e32 v195, v195
	v_rcp_f32_e32 v196, v196
	v_rcp_f32_e32 v197, v197
	v_pk_mul_f32 v[100:101], v[100:101], v[190:191]
	v_pk_mul_f32 v[102:103], v[102:103], v[192:193]
	v_pk_mul_f32 v[96:97], v[96:97], v[194:195]
	v_pk_mul_f32 v[98:99], v[98:99], v[196:197]
	v_pk_mul_f32 v[100:101], v[100:101], v[92:93]
	v_pk_mul_f32 v[102:103], v[102:103], v[94:95]
	v_pk_mul_f32 v[96:97], v[96:97], v[88:89]
	v_pk_mul_f32 v[98:99], v[98:99], v[90:91]
	v_cvt_pk_bf16_f32 v198, v100, v101
	v_cvt_pk_bf16_f32 v199, v102, v103
	v_cvt_pk_bf16_f32 v200, v96, v97
	v_cvt_pk_bf16_f32 v201, v98, v99
	v_add_u32_e32 v203, 0x2c000, v202
	s_nop 0
	global_store_dwordx4 v203, v[198:201], s[6:7] sc1
	v_pk_fma_f32 v[84:85], v[84:85], v[184:185], v[238:239] op_sel:[0,1,0] op_sel_hi:[1,1,1]
	v_pk_fma_f32 v[86:87], v[86:87], v[184:185], v[240:241] op_sel:[0,1,0] op_sel_hi:[1,1,1]
	v_pk_fma_f32 v[80:81], v[80:81], v[184:185], v[242:243] op_sel:[0,1,0] op_sel_hi:[1,1,1]
	v_pk_fma_f32 v[82:83], v[82:83], v[184:185], v[244:245] op_sel:[0,1,0] op_sel_hi:[1,1,1]
	v_pk_fma_f32 v[76:77], v[76:77], v[184:185], v[246:247] op_sel:[0,1,0] op_sel_hi:[1,1,1]
	v_pk_fma_f32 v[78:79], v[78:79], v[184:185], v[248:249] op_sel:[0,1,0] op_sel_hi:[1,1,1]
	v_pk_fma_f32 v[72:73], v[72:73], v[184:185], v[250:251] op_sel:[0,1,0] op_sel_hi:[1,1,1]
	v_pk_fma_f32 v[74:75], v[74:75], v[184:185], v[252:253] op_sel:[0,1,0] op_sel_hi:[1,1,1]
	v_pk_mul_f32 v[190:191], v[84:85], v[178:179]
	v_pk_mul_f32 v[192:193], v[86:87], v[178:179]
	v_pk_mul_f32 v[194:195], v[80:81], v[178:179]
	v_pk_mul_f32 v[196:197], v[82:83], v[178:179]
	v_exp_f32_e32 v190, v190
	v_exp_f32_e32 v191, v191
	v_exp_f32_e32 v192, v192
	v_exp_f32_e32 v193, v193
	v_exp_f32_e32 v194, v194
	v_exp_f32_e32 v195, v195
	v_exp_f32_e32 v196, v196
	v_exp_f32_e32 v197, v197
	v_pk_add_f32 v[190:191], v[190:191], 1.0 op_sel_hi:[1,0]
	v_pk_add_f32 v[192:193], v[192:193], 1.0 op_sel_hi:[1,0]
	v_pk_add_f32 v[194:195], v[194:195], 1.0 op_sel_hi:[1,0]
	v_pk_add_f32 v[196:197], v[196:197], 1.0 op_sel_hi:[1,0]
	v_rcp_f32_e32 v190, v190
	v_rcp_f32_e32 v191, v191
	v_rcp_f32_e32 v192, v192
	v_rcp_f32_e32 v193, v193
	v_rcp_f32_e32 v194, v194
	v_rcp_f32_e32 v195, v195
	v_rcp_f32_e32 v196, v196
	v_rcp_f32_e32 v197, v197
	v_pk_mul_f32 v[84:85], v[84:85], v[190:191]
	v_pk_mul_f32 v[86:87], v[86:87], v[192:193]
	v_pk_mul_f32 v[80:81], v[80:81], v[194:195]
	v_pk_mul_f32 v[82:83], v[82:83], v[196:197]
	v_pk_mul_f32 v[84:85], v[84:85], v[76:77]
	v_pk_mul_f32 v[86:87], v[86:87], v[78:79]
	v_pk_mul_f32 v[80:81], v[80:81], v[72:73]
	v_pk_mul_f32 v[82:83], v[82:83], v[74:75]
	v_cvt_pk_bf16_f32 v198, v84, v85
	v_cvt_pk_bf16_f32 v199, v86, v87
	v_cvt_pk_bf16_f32 v200, v80, v81
	v_cvt_pk_bf16_f32 v201, v82, v83
	v_add_u32_e32 v203, 0x42000, v202
	s_nop 0
	global_store_dwordx4 v203, v[198:201], s[6:7] sc1
	v_pk_fma_f32 v[68:69], v[68:69], v[186:187], v[238:239] op_sel_hi:[1,0,1]
	v_pk_fma_f32 v[70:71], v[70:71], v[186:187], v[240:241] op_sel_hi:[1,0,1]
	v_pk_fma_f32 v[64:65], v[64:65], v[186:187], v[242:243] op_sel_hi:[1,0,1]
	v_pk_fma_f32 v[66:67], v[66:67], v[186:187], v[244:245] op_sel_hi:[1,0,1]
	v_pk_fma_f32 v[60:61], v[60:61], v[186:187], v[246:247] op_sel_hi:[1,0,1]
	v_pk_fma_f32 v[62:63], v[62:63], v[186:187], v[248:249] op_sel_hi:[1,0,1]
	v_pk_fma_f32 v[52:53], v[52:53], v[186:187], v[250:251] op_sel_hi:[1,0,1]
	v_pk_fma_f32 v[54:55], v[54:55], v[186:187], v[252:253] op_sel_hi:[1,0,1]
	v_pk_mul_f32 v[190:191], v[68:69], v[178:179]
	v_pk_mul_f32 v[192:193], v[70:71], v[178:179]
	v_pk_mul_f32 v[194:195], v[64:65], v[178:179]
	v_pk_mul_f32 v[196:197], v[66:67], v[178:179]
	v_exp_f32_e32 v190, v190
	v_exp_f32_e32 v191, v191
	v_exp_f32_e32 v192, v192
	v_exp_f32_e32 v193, v193
	v_exp_f32_e32 v194, v194
	v_exp_f32_e32 v195, v195
	v_exp_f32_e32 v196, v196
	v_exp_f32_e32 v197, v197
	v_pk_add_f32 v[190:191], v[190:191], 1.0 op_sel_hi:[1,0]
	v_pk_add_f32 v[192:193], v[192:193], 1.0 op_sel_hi:[1,0]
	v_pk_add_f32 v[194:195], v[194:195], 1.0 op_sel_hi:[1,0]
	v_pk_add_f32 v[196:197], v[196:197], 1.0 op_sel_hi:[1,0]
	v_rcp_f32_e32 v190, v190
	v_rcp_f32_e32 v191, v191
	v_rcp_f32_e32 v192, v192
	v_rcp_f32_e32 v193, v193
	v_rcp_f32_e32 v194, v194
	v_rcp_f32_e32 v195, v195
	v_rcp_f32_e32 v196, v196
	v_rcp_f32_e32 v197, v197
	v_pk_mul_f32 v[68:69], v[68:69], v[190:191]
	v_pk_mul_f32 v[70:71], v[70:71], v[192:193]
	v_pk_mul_f32 v[64:65], v[64:65], v[194:195]
	v_pk_mul_f32 v[66:67], v[66:67], v[196:197]
	v_pk_mul_f32 v[68:69], v[68:69], v[60:61]
	v_pk_mul_f32 v[70:71], v[70:71], v[62:63]
	v_pk_mul_f32 v[64:65], v[64:65], v[52:53]
	v_pk_mul_f32 v[66:67], v[66:67], v[54:55]
	v_cvt_pk_bf16_f32 v198, v68, v69
	v_cvt_pk_bf16_f32 v199, v70, v71
	v_cvt_pk_bf16_f32 v200, v64, v65
	v_cvt_pk_bf16_f32 v201, v66, v67
	v_add_u32_e32 v203, 0xb0000, v202
	s_nop 0
	global_store_dwordx4 v203, v[198:201], s[6:7] sc1
	v_pk_fma_f32 v[44:45], v[44:45], v[186:187], v[238:239] op_sel:[0,1,0] op_sel_hi:[1,1,1]
	v_pk_fma_f32 v[46:47], v[46:47], v[186:187], v[240:241] op_sel:[0,1,0] op_sel_hi:[1,1,1]
	v_pk_fma_f32 v[40:41], v[40:41], v[186:187], v[242:243] op_sel:[0,1,0] op_sel_hi:[1,1,1]
	v_pk_fma_f32 v[42:43], v[42:43], v[186:187], v[244:245] op_sel:[0,1,0] op_sel_hi:[1,1,1]
	v_pk_fma_f32 v[36:37], v[36:37], v[186:187], v[246:247] op_sel:[0,1,0] op_sel_hi:[1,1,1]
	v_pk_fma_f32 v[38:39], v[38:39], v[186:187], v[248:249] op_sel:[0,1,0] op_sel_hi:[1,1,1]
	v_pk_fma_f32 v[32:33], v[32:33], v[186:187], v[250:251] op_sel:[0,1,0] op_sel_hi:[1,1,1]
	v_pk_fma_f32 v[34:35], v[34:35], v[186:187], v[252:253] op_sel:[0,1,0] op_sel_hi:[1,1,1]
	v_pk_mul_f32 v[190:191], v[44:45], v[178:179]
	v_pk_mul_f32 v[192:193], v[46:47], v[178:179]
	v_pk_mul_f32 v[194:195], v[40:41], v[178:179]
	v_pk_mul_f32 v[196:197], v[42:43], v[178:179]
	v_exp_f32_e32 v190, v190
	v_exp_f32_e32 v191, v191
	v_exp_f32_e32 v192, v192
	v_exp_f32_e32 v193, v193
	v_exp_f32_e32 v194, v194
	v_exp_f32_e32 v195, v195
	v_exp_f32_e32 v196, v196
	v_exp_f32_e32 v197, v197
	v_pk_add_f32 v[190:191], v[190:191], 1.0 op_sel_hi:[1,0]
	v_pk_add_f32 v[192:193], v[192:193], 1.0 op_sel_hi:[1,0]
	v_pk_add_f32 v[194:195], v[194:195], 1.0 op_sel_hi:[1,0]
	v_pk_add_f32 v[196:197], v[196:197], 1.0 op_sel_hi:[1,0]
	v_rcp_f32_e32 v190, v190
	v_rcp_f32_e32 v191, v191
	v_rcp_f32_e32 v192, v192
	v_rcp_f32_e32 v193, v193
	v_rcp_f32_e32 v194, v194
	v_rcp_f32_e32 v195, v195
	v_rcp_f32_e32 v196, v196
	v_rcp_f32_e32 v197, v197
	v_pk_mul_f32 v[44:45], v[44:45], v[190:191]
	v_pk_mul_f32 v[46:47], v[46:47], v[192:193]
	v_pk_mul_f32 v[40:41], v[40:41], v[194:195]
	v_pk_mul_f32 v[42:43], v[42:43], v[196:197]
	v_pk_mul_f32 v[44:45], v[44:45], v[36:37]
	v_pk_mul_f32 v[46:47], v[46:47], v[38:39]
	v_pk_mul_f32 v[40:41], v[40:41], v[32:33]
	v_pk_mul_f32 v[42:43], v[42:43], v[34:35]
	v_cvt_pk_bf16_f32 v198, v44, v45
	v_cvt_pk_bf16_f32 v199, v46, v47
	v_cvt_pk_bf16_f32 v200, v40, v41
	v_cvt_pk_bf16_f32 v201, v42, v43
	v_add_u32_e32 v203, 0xc6000, v202
	s_nop 0
	global_store_dwordx4 v203, v[198:201], s[6:7] sc1
	v_pk_fma_f32 v[28:29], v[28:29], v[188:189], v[238:239] op_sel_hi:[1,0,1]
	v_pk_fma_f32 v[30:31], v[30:31], v[188:189], v[240:241] op_sel_hi:[1,0,1]
	v_pk_fma_f32 v[24:25], v[24:25], v[188:189], v[242:243] op_sel_hi:[1,0,1]
	v_pk_fma_f32 v[26:27], v[26:27], v[188:189], v[244:245] op_sel_hi:[1,0,1]
	v_pk_fma_f32 v[20:21], v[20:21], v[188:189], v[246:247] op_sel_hi:[1,0,1]
	v_pk_fma_f32 v[22:23], v[22:23], v[188:189], v[248:249] op_sel_hi:[1,0,1]
	v_pk_fma_f32 v[16:17], v[16:17], v[188:189], v[250:251] op_sel_hi:[1,0,1]
	v_pk_fma_f32 v[18:19], v[18:19], v[188:189], v[252:253] op_sel_hi:[1,0,1]
	v_pk_mul_f32 v[190:191], v[28:29], v[178:179]
	v_pk_mul_f32 v[192:193], v[30:31], v[178:179]
	v_pk_mul_f32 v[194:195], v[24:25], v[178:179]
	v_pk_mul_f32 v[196:197], v[26:27], v[178:179]
	v_exp_f32_e32 v190, v190
	v_exp_f32_e32 v191, v191
	v_exp_f32_e32 v192, v192
	v_exp_f32_e32 v193, v193
	v_exp_f32_e32 v194, v194
	v_exp_f32_e32 v195, v195
	v_exp_f32_e32 v196, v196
	v_exp_f32_e32 v197, v197
	v_pk_add_f32 v[190:191], v[190:191], 1.0 op_sel_hi:[1,0]
	v_pk_add_f32 v[192:193], v[192:193], 1.0 op_sel_hi:[1,0]
	v_pk_add_f32 v[194:195], v[194:195], 1.0 op_sel_hi:[1,0]
	v_pk_add_f32 v[196:197], v[196:197], 1.0 op_sel_hi:[1,0]
	v_rcp_f32_e32 v190, v190
	v_rcp_f32_e32 v191, v191
	v_rcp_f32_e32 v192, v192
	v_rcp_f32_e32 v193, v193
	v_rcp_f32_e32 v194, v194
	v_rcp_f32_e32 v195, v195
	v_rcp_f32_e32 v196, v196
	v_rcp_f32_e32 v197, v197
	v_pk_mul_f32 v[28:29], v[28:29], v[190:191]
	v_pk_mul_f32 v[30:31], v[30:31], v[192:193]
	v_pk_mul_f32 v[24:25], v[24:25], v[194:195]
	v_pk_mul_f32 v[26:27], v[26:27], v[196:197]
	v_pk_mul_f32 v[28:29], v[28:29], v[20:21]
	v_pk_mul_f32 v[30:31], v[30:31], v[22:23]
	v_pk_mul_f32 v[24:25], v[24:25], v[16:17]
	v_pk_mul_f32 v[26:27], v[26:27], v[18:19]
	v_cvt_pk_bf16_f32 v198, v28, v29
	v_cvt_pk_bf16_f32 v199, v30, v31
	v_cvt_pk_bf16_f32 v200, v24, v25
	v_cvt_pk_bf16_f32 v201, v26, v27
	v_add_u32_e32 v203, 0xdc000, v202
	s_nop 0
	global_store_dwordx4 v203, v[198:201], s[6:7] sc1
	v_pk_fma_f32 v[12:13], v[12:13], v[188:189], v[238:239] op_sel:[0,1,0] op_sel_hi:[1,1,1]
	v_pk_fma_f32 v[14:15], v[14:15], v[188:189], v[240:241] op_sel:[0,1,0] op_sel_hi:[1,1,1]
	v_pk_fma_f32 v[8:9], v[8:9], v[188:189], v[242:243] op_sel:[0,1,0] op_sel_hi:[1,1,1]
	v_pk_fma_f32 v[10:11], v[10:11], v[188:189], v[244:245] op_sel:[0,1,0] op_sel_hi:[1,1,1]
	v_pk_fma_f32 v[4:5], v[4:5], v[188:189], v[246:247] op_sel:[0,1,0] op_sel_hi:[1,1,1]
	v_pk_fma_f32 v[6:7], v[6:7], v[188:189], v[248:249] op_sel:[0,1,0] op_sel_hi:[1,1,1]
	v_pk_fma_f32 v[0:1], v[0:1], v[188:189], v[250:251] op_sel:[0,1,0] op_sel_hi:[1,1,1]
	v_pk_fma_f32 v[2:3], v[2:3], v[188:189], v[252:253] op_sel:[0,1,0] op_sel_hi:[1,1,1]
	v_pk_mul_f32 v[190:191], v[12:13], v[178:179]
	v_pk_mul_f32 v[192:193], v[14:15], v[178:179]
	v_pk_mul_f32 v[194:195], v[8:9], v[178:179]
	v_pk_mul_f32 v[196:197], v[10:11], v[178:179]
	v_exp_f32_e32 v190, v190
	v_exp_f32_e32 v191, v191
	v_exp_f32_e32 v192, v192
	v_exp_f32_e32 v193, v193
	v_exp_f32_e32 v194, v194
	v_exp_f32_e32 v195, v195
	v_exp_f32_e32 v196, v196
	v_exp_f32_e32 v197, v197
	v_pk_add_f32 v[190:191], v[190:191], 1.0 op_sel_hi:[1,0]
	v_pk_add_f32 v[192:193], v[192:193], 1.0 op_sel_hi:[1,0]
	v_pk_add_f32 v[194:195], v[194:195], 1.0 op_sel_hi:[1,0]
	v_pk_add_f32 v[196:197], v[196:197], 1.0 op_sel_hi:[1,0]
	v_rcp_f32_e32 v190, v190
	v_rcp_f32_e32 v191, v191
	v_rcp_f32_e32 v192, v192
	v_rcp_f32_e32 v193, v193
	v_rcp_f32_e32 v194, v194
	v_rcp_f32_e32 v195, v195
	v_rcp_f32_e32 v196, v196
	v_rcp_f32_e32 v197, v197
	v_pk_mul_f32 v[12:13], v[12:13], v[190:191]
	v_pk_mul_f32 v[14:15], v[14:15], v[192:193]
	v_pk_mul_f32 v[8:9], v[8:9], v[194:195]
	v_pk_mul_f32 v[10:11], v[10:11], v[196:197]
	v_pk_mul_f32 v[12:13], v[12:13], v[4:5]
	v_pk_mul_f32 v[14:15], v[14:15], v[6:7]
	v_pk_mul_f32 v[8:9], v[8:9], v[0:1]
	v_pk_mul_f32 v[10:11], v[10:11], v[2:3]
	v_cvt_pk_bf16_f32 v198, v12, v13
	v_cvt_pk_bf16_f32 v199, v14, v15
	v_cvt_pk_bf16_f32 v200, v8, v9
	v_cvt_pk_bf16_f32 v201, v10, v11
	v_add_u32_e32 v203, 0xf2000, v202
	s_nop 0
	global_store_dwordx4 v203, v[198:201], s[6:7] sc1
	s_andn2_b64 vcc, exec, s[4:5]
	s_cbranch_vccnz .LBB0_248
	s_andn2_b64 vcc, exec, s[0:1]
	s_cbranch_vccnz .LBB0_247
	s_barrier
	s_branch .LBB0_247
